# v54 + short common-path back edge for the rotated Up/MixIn K-loops (exit test and last-step check skipped when more than one K-step pair remains)
# baseline (speedup 1.0000x reference)
; #define PG8_STAGE(bufoff, gbase, voff) do { _Pragma("unroll") for (int _i = 0; _i < 2; ++_i) \
;         __builtin_amdgcn_global_load_lds((const unsigned*)((const char*)(gbase) + (voff)[_i]), (PG8_LAS unsigned*)(lds + (bufoff) + ldsw + _i * (8 * USTR)), 16, 0, 0); } while (0)
; #define PG8_LDA(dst, b, h) do { _Pragma("unroll") for (int m = 0; m < 4; ++m) _Pragma("unroll") for (int k = 0; k < 2; ++k) dst[m][k] = *(const PG8_LAS bf16x8*)(lds + PG8_SA(b, h) + aoff + m * (2 * USTR) + k * 64); } while (0)
; #define PG8_LDB(dst, b, h) do { _Pragma("unroll") for (int n = 0; n < 2; ++n) _Pragma("unroll") for (int k = 0; k < 2; ++k) dst[n][k] = *(const PG8_LAS bf16x8*)(lds + PG8_SB(b, h) + boff + n * (2 * USTR) + k * 64); } while (0)
; #define PG8_MMA(ai, bj, At, Bt) do { __builtin_amdgcn_s_setprio(1); _Pragma("unroll") for (int m = 0; m < 4; ++m) _Pragma("unroll") for (int n = 0; n < 2; ++n) _Pragma("unroll") for (int k = 0; k < 2; ++k) \
;         acc[ai][bj][m][n] = __builtin_amdgcn_mfma_f32_16x16x32_bf16(Bt[n][k], At[m][k], acc[ai][bj][m][n], 0, 0, 0); __builtin_amdgcn_s_setprio(0); } while (0)
; #define PG8_WAIT_V(n) asm volatile("s_waitcnt vmcnt(" #n ")" ::: "memory")
; #define PG8_WAIT_L(n) asm volatile("s_waitcnt lgkmcnt(" #n ")" ::: "memory")
; #define PG8_BAR __builtin_amdgcn_s_barrier()
; #define PG8_SCHED __builtin_amdgcn_sched_barrier(0)
; template <class Epi, class Sched, bool ALIGN_EPI, bool SP2>
; __device__ __forceinline__ void gemm_phase(PG8_LAS unsigned char* lds, const Gemm g, const Sched& S, const Epi& E, int wid) {
;     ...
;             PG8_LDB(B0, 0, 0); PG8_LDB(B1, 0, 1); PG8_SCHED; PG8_LDA(At, 0, 0); PG8_STAGE(PG8_SA(1, 1), a1 + hstepA, voffA);
;             PG8_WAIT_V(8); PG8_WAIT_L(0); PG8_BAR; PG8_MMA(0, 0, At, B0); PG8_MMA(0, 1, At, B1); PG8_BAR; PG8_SCHED;
;             PG8_LDA(At, 0, 1); PG8_STAGE(PG8_SB(0, 0), b2, voffB); PG8_STAGE(PG8_SB(0, 1), b2 + hstepB, voffB); PG8_STAGE(PG8_SA(0, 0), a2, voffA);
;             PG8_WAIT_V(8); PG8_WAIT_L(0); PG8_BAR; PG8_MMA(1, 0, At, B0); PG8_MMA(1, 1, At, B1); PG8_BAR; PG8_SCHED;
.LBB0_373:
	v_add_u32_e32 v94, 0x11000, v161
	ds_read_b128 v[86:89], v94
	ds_read_b128 v[90:93], v94 offset:64
	ds_read_b128 v[164:167], v94 offset:2176
	ds_read_b128 v[168:171], v94 offset:2240
	v_add_u32_e32 v94, 0x15400, v161
	ds_read_b128 v[172:175], v94
	ds_read_b128 v[176:179], v94 offset:64
	ds_read_b128 v[180:183], v94 offset:2176
	ds_read_b128 v[184:187], v94 offset:2240
	s_add_i32 s77, 0, 0x11000
	s_add_i32 s89, 0, 0x15400
	v_lshl_add_u64 v[94:95], s[38:39], 0, v[154:155]
	s_add_i32 m0, s0, 0xcc00
	ds_read_b128 v[188:191], v163
	ds_read_b128 v[208:211], v163 offset:64
	ds_read_b128 v[212:215], v163 offset:2176
	ds_read_b128 v[216:219], v163 offset:2240
	ds_read_b128 v[220:223], v163 offset:4352
	ds_read_b128 v[224:227], v163 offset:4416
	ds_read_b128 v[228:231], v163 offset:6528
	ds_read_b128 v[242:245], v163 offset:6592
	global_load_lds_dwordx4 v[94:95], off
	v_lshl_add_u64 v[94:95], s[38:39], 0, v[156:157]
	s_add_i32 m0, s0, 0xee00
	s_nop 0
	global_load_lds_dwordx4 v[94:95], off
	s_add_u32 s70, s38, 0xfffc0080
	s_addc_u32 s71, s39, -1
	s_and_b64 s[68:69], s[68:69], exec
	s_cselect_b32 s71, s26, s71
	s_cselect_b32 s70, s27, s70
	s_cselect_b32 s69, s41, s75
	s_cselect_b32 s68, s73, s74
	s_waitcnt vmcnt(8)
	s_waitcnt lgkmcnt(0)
	s_barrier
	s_setprio 1
	s_waitcnt lgkmcnt(0)
	v_mfma_f32_16x16x32_bf16 v[140:143], v[86:89], v[188:191], v[140:143]
	v_mfma_f32_16x16x32_bf16 v[136:139], v[164:167], v[188:191], v[136:139]
	v_mfma_f32_16x16x32_bf16 v[124:127], v[86:89], v[212:215], v[124:127]
	v_mfma_f32_16x16x32_bf16 v[120:123], v[164:167], v[212:215], v[120:123]
	v_mfma_f32_16x16x32_bf16 v[108:111], v[86:89], v[220:223], v[108:111]
	v_mfma_f32_16x16x32_bf16 v[104:107], v[164:167], v[220:223], v[104:107]
	v_mfma_f32_16x16x32_bf16 v[76:79], v[86:89], v[228:231], v[76:79]
	v_mfma_f32_16x16x32_bf16 v[72:75], v[164:167], v[228:231], v[72:75]
	v_mfma_f32_16x16x32_bf16 v[140:143], v[90:93], v[208:211], v[140:143]
	v_mfma_f32_16x16x32_bf16 v[136:139], v[168:171], v[208:211], v[136:139]
	v_mfma_f32_16x16x32_bf16 v[124:127], v[90:93], v[216:219], v[124:127]
	v_mfma_f32_16x16x32_bf16 v[120:123], v[168:171], v[216:219], v[120:123]
	v_mfma_f32_16x16x32_bf16 v[108:111], v[90:93], v[224:227], v[108:111]
	v_mfma_f32_16x16x32_bf16 v[104:107], v[168:171], v[224:227], v[104:107]
	v_mfma_f32_16x16x32_bf16 v[76:79], v[90:93], v[242:245], v[76:79]
	v_mfma_f32_16x16x32_bf16 v[72:75], v[168:171], v[242:245], v[72:75]
	s_setprio 0
	s_setprio 1
	v_mfma_f32_16x16x32_bf16 v[132:135], v[172:175], v[188:191], v[132:135]
	v_mfma_f32_16x16x32_bf16 v[128:131], v[180:183], v[188:191], v[128:131]
	v_mfma_f32_16x16x32_bf16 v[116:119], v[172:175], v[212:215], v[116:119]
	v_mfma_f32_16x16x32_bf16 v[112:115], v[180:183], v[212:215], v[112:115]
	v_mfma_f32_16x16x32_bf16 v[100:103], v[172:175], v[220:223], v[100:103]
	v_mfma_f32_16x16x32_bf16 v[94:97], v[180:183], v[220:223], v[96:99]
	v_mfma_f32_16x16x32_bf16 v[68:71], v[172:175], v[228:231], v[68:71]
	v_mfma_f32_16x16x32_bf16 v[64:67], v[180:183], v[228:231], v[64:67]
	v_mfma_f32_16x16x32_bf16 v[132:135], v[176:179], v[208:211], v[132:135]
	v_mfma_f32_16x16x32_bf16 v[128:131], v[184:187], v[208:211], v[128:131]
	v_mfma_f32_16x16x32_bf16 v[116:119], v[176:179], v[216:219], v[116:119]
	v_mfma_f32_16x16x32_bf16 v[112:115], v[184:187], v[216:219], v[112:115]
	v_mfma_f32_16x16x32_bf16 v[100:103], v[176:179], v[224:227], v[100:103]
	v_mfma_f32_16x16x32_bf16 v[94:97], v[184:187], v[224:227], v[94:97]
	v_mfma_f32_16x16x32_bf16 v[68:71], v[176:179], v[242:245], v[68:71]
	v_mfma_f32_16x16x32_bf16 v[64:67], v[184:187], v[242:245], v[64:67]
	s_setprio 0
	s_barrier
	s_add_i32 s77, s77, s33
	v_lshl_add_u64 v[158:159], s[68:69], 0, v[192:193]
	s_mov_b32 m0, s77
	ds_read_b128 v[188:191], v163 offset:17408
	ds_read_b128 v[208:211], v163 offset:17472
	ds_read_b128 v[212:215], v163 offset:19584
	ds_read_b128 v[216:219], v163 offset:19648
	ds_read_b128 v[220:223], v163 offset:21760
	ds_read_b128 v[224:227], v163 offset:21824
	ds_read_b128 v[228:231], v163 offset:23936
	ds_read_b128 v[242:245], v163 offset:24000
	global_load_lds_dwordx4 v[158:159], off
	s_add_i32 m0, s77, 0x2200
	s_add_u32 s78, s68, 0x40000
	v_lshl_add_u64 v[198:199], s[68:69], 0, v[144:145]
	s_addc_u32 s79, s69, 0
	s_add_i32 s77, s89, s33
	global_load_lds_dwordx4 v[198:199], off
	v_lshl_add_u64 v[98:99], s[78:79], 0, v[192:193]
	s_mov_b32 m0, s77
	v_lshl_add_u64 v[200:201], s[70:71], 0, v[148:149]
	global_load_lds_dwordx4 v[98:99], off
	v_lshl_add_u64 v[98:99], s[78:79], 0, v[144:145]
	s_add_i32 m0, s77, 0x2200
	v_lshl_add_u64 v[232:233], s[70:71], 0, v[146:147]
	global_load_lds_dwordx4 v[98:99], off
	s_mov_b32 m0, s0
	s_nop 0
	global_load_lds_dwordx4 v[200:201], off
	s_mov_b32 m0, s5
	s_nop 0
	global_load_lds_dwordx4 v[232:233], off
	s_waitcnt vmcnt(8)
	s_waitcnt lgkmcnt(0)
	s_barrier
; #define PG8_STAGE(bufoff, gbase, voff) do { _Pragma("unroll") for (int _i = 0; _i < 2; ++_i) \
;         __builtin_amdgcn_global_load_lds((const unsigned*)((const char*)(gbase) + (voff)[_i]), (PG8_LAS unsigned*)(lds + (bufoff) + ldsw + _i * (8 * USTR)), 16, 0, 0); } while (0)
; #define PG8_LDA(dst, b, h) do { _Pragma("unroll") for (int m = 0; m < 4; ++m) _Pragma("unroll") for (int k = 0; k < 2; ++k) dst[m][k] = *(const PG8_LAS bf16x8*)(lds + PG8_SA(b, h) + aoff + m * (2 * USTR) + k * 64); } while (0)
; #define PG8_LDB(dst, b, h) do { _Pragma("unroll") for (int n = 0; n < 2; ++n) _Pragma("unroll") for (int k = 0; k < 2; ++k) dst[n][k] = *(const PG8_LAS bf16x8*)(lds + PG8_SB(b, h) + boff + n * (2 * USTR) + k * 64); } while (0)
; #define PG8_MMA(ai, bj, At, Bt) do { __builtin_amdgcn_s_setprio(1); _Pragma("unroll") for (int m = 0; m < 4; ++m) _Pragma("unroll") for (int n = 0; n < 2; ++n) _Pragma("unroll") for (int k = 0; k < 2; ++k) \
;         acc[ai][bj][m][n] = __builtin_amdgcn_mfma_f32_16x16x32_bf16(Bt[n][k], At[m][k], acc[ai][bj][m][n], 0, 0, 0); __builtin_amdgcn_s_setprio(0); } while (0)
; #define PG8_WAIT_V(n) asm volatile("s_waitcnt vmcnt(" #n ")" ::: "memory")
; #define PG8_WAIT_L(n) asm volatile("s_waitcnt lgkmcnt(" #n ")" ::: "memory")
; #define PG8_BAR __builtin_amdgcn_s_barrier()
; #define PG8_SCHED __builtin_amdgcn_sched_barrier(0)
; template <class Epi, class Sched, bool ALIGN_EPI, bool SP2>
; __device__ __forceinline__ void gemm_phase(PG8_LAS unsigned char* lds, const Gemm g, const Sched& S, const Epi& E, int wid) {
;     ...
;             PG8_WAIT_V(8); PG8_WAIT_L(0); PG8_BAR; PG8_MMA(1, 0, At, B0); PG8_MMA(1, 1, At, B1); PG8_BAR; PG8_SCHED;
;             PG8_LDB(B0, 1, 0); PG8_LDB(B1, 1, 1); PG8_SCHED; PG8_LDA(At, 1, 0); PG8_STAGE(PG8_SA(0, 1), a2 + hstepA, voffA);
;             PG8_WAIT_V(8); PG8_WAIT_L(0); PG8_BAR; PG8_MMA(0, 0, At, B0); PG8_MMA(0, 1, At, B1); PG8_BAR; PG8_SCHED;
	s_setprio 1
	s_waitcnt lgkmcnt(0)
	v_mfma_f32_16x16x32_bf16 v[60:63], v[86:89], v[188:191], v[60:63]
	v_mfma_f32_16x16x32_bf16 v[56:59], v[164:167], v[188:191], v[56:59]
	v_mfma_f32_16x16x32_bf16 v[44:47], v[86:89], v[212:215], v[44:47]
	v_mfma_f32_16x16x32_bf16 v[40:43], v[164:167], v[212:215], v[40:43]
	v_mfma_f32_16x16x32_bf16 v[28:31], v[86:89], v[220:223], v[28:31]
	v_mfma_f32_16x16x32_bf16 v[24:27], v[164:167], v[220:223], v[24:27]
	v_mfma_f32_16x16x32_bf16 v[12:15], v[86:89], v[228:231], v[12:15]
	v_mfma_f32_16x16x32_bf16 v[8:11], v[164:167], v[228:231], v[8:11]
	v_mfma_f32_16x16x32_bf16 v[60:63], v[90:93], v[208:211], v[60:63]
	v_mfma_f32_16x16x32_bf16 v[56:59], v[168:171], v[208:211], v[56:59]
	v_mfma_f32_16x16x32_bf16 v[44:47], v[90:93], v[216:219], v[44:47]
	v_mfma_f32_16x16x32_bf16 v[40:43], v[168:171], v[216:219], v[40:43]
	v_mfma_f32_16x16x32_bf16 v[28:31], v[90:93], v[224:227], v[28:31]
	v_mfma_f32_16x16x32_bf16 v[24:27], v[168:171], v[224:227], v[24:27]
	v_mfma_f32_16x16x32_bf16 v[12:15], v[90:93], v[242:245], v[12:15]
	v_mfma_f32_16x16x32_bf16 v[8:11], v[168:171], v[242:245], v[8:11]
	s_setprio 0
	s_setprio 1
	v_mfma_f32_16x16x32_bf16 v[52:55], v[172:175], v[188:191], v[52:55]
	v_mfma_f32_16x16x32_bf16 v[48:51], v[180:183], v[188:191], v[48:51]
	v_mfma_f32_16x16x32_bf16 v[36:39], v[172:175], v[212:215], v[36:39]
	v_mfma_f32_16x16x32_bf16 v[32:35], v[180:183], v[212:215], v[32:35]
	v_mfma_f32_16x16x32_bf16 v[20:23], v[172:175], v[220:223], v[20:23]
	v_mfma_f32_16x16x32_bf16 v[16:19], v[180:183], v[220:223], v[16:19]
	v_mfma_f32_16x16x32_bf16 v[4:7], v[172:175], v[228:231], v[4:7]
	v_mfma_f32_16x16x32_bf16 v[0:3], v[180:183], v[228:231], v[0:3]
	v_mfma_f32_16x16x32_bf16 v[52:55], v[176:179], v[208:211], v[52:55]
	v_mfma_f32_16x16x32_bf16 v[48:51], v[184:187], v[208:211], v[48:51]
	v_mfma_f32_16x16x32_bf16 v[36:39], v[176:179], v[216:219], v[36:39]
	v_mfma_f32_16x16x32_bf16 v[32:35], v[184:187], v[216:219], v[32:35]
	v_mfma_f32_16x16x32_bf16 v[20:23], v[176:179], v[224:227], v[20:23]
	v_mfma_f32_16x16x32_bf16 v[16:19], v[184:187], v[224:227], v[16:19]
	v_mfma_f32_16x16x32_bf16 v[4:7], v[176:179], v[242:245], v[4:7]
	v_mfma_f32_16x16x32_bf16 v[0:3], v[184:187], v[242:245], v[0:3]
	s_setprio 0
	s_barrier
	v_add_u32_e32 v98, 0x19800, v161
	ds_read_b128 v[86:89], v98
	ds_read_b128 v[90:93], v98 offset:64
	ds_read_b128 v[164:167], v98 offset:2176
	ds_read_b128 v[168:171], v98 offset:2240
	v_add_u32_e32 v98, 0x1dc00, v161
	ds_read_b128 v[172:175], v98
	ds_read_b128 v[176:179], v98 offset:64
	ds_read_b128 v[180:183], v98 offset:2176
	ds_read_b128 v[184:187], v98 offset:2240
	s_add_i32 s77, 0, 0x19800
	s_add_i32 s78, 0, 0x1dc00
	s_add_u32 s70, s70, 0x40000
	s_addc_u32 s71, s71, 0
	s_mov_b32 m0, s10
	v_lshl_add_u64 v[98:99], s[70:71], 0, v[148:149]
	ds_read_b128 v[188:191], v163 offset:34816
	ds_read_b128 v[208:211], v163 offset:34880
	ds_read_b128 v[212:215], v163 offset:36992
	ds_read_b128 v[216:219], v163 offset:37056
	ds_read_b128 v[220:223], v163 offset:39168
	ds_read_b128 v[224:227], v163 offset:39232
	ds_read_b128 v[228:231], v163 offset:41344
	ds_read_b128 v[242:245], v163 offset:41408
	global_load_lds_dwordx4 v[98:99], off
	v_lshl_add_u64 v[98:99], s[70:71], 0, v[146:147]
	s_mov_b32 m0, s29
	s_nop 0
	global_load_lds_dwordx4 v[98:99], off
	s_waitcnt vmcnt(8)
	s_waitcnt lgkmcnt(0)
	s_barrier
	s_setprio 1
	s_waitcnt lgkmcnt(0)
	v_mfma_f32_16x16x32_bf16 v[140:143], v[86:89], v[188:191], v[140:143]
	v_mfma_f32_16x16x32_bf16 v[136:139], v[164:167], v[188:191], v[136:139]
	v_mfma_f32_16x16x32_bf16 v[124:127], v[86:89], v[212:215], v[124:127]
	v_mfma_f32_16x16x32_bf16 v[120:123], v[164:167], v[212:215], v[120:123]
	v_mfma_f32_16x16x32_bf16 v[108:111], v[86:89], v[220:223], v[108:111]
	v_mfma_f32_16x16x32_bf16 v[104:107], v[164:167], v[220:223], v[104:107]
	v_mfma_f32_16x16x32_bf16 v[76:79], v[86:89], v[228:231], v[76:79]
	v_mfma_f32_16x16x32_bf16 v[72:75], v[164:167], v[228:231], v[72:75]
	v_mfma_f32_16x16x32_bf16 v[140:143], v[90:93], v[208:211], v[140:143]
	v_mfma_f32_16x16x32_bf16 v[136:139], v[168:171], v[208:211], v[136:139]
	v_mfma_f32_16x16x32_bf16 v[124:127], v[90:93], v[216:219], v[124:127]
	v_mfma_f32_16x16x32_bf16 v[120:123], v[168:171], v[216:219], v[120:123]
	v_mfma_f32_16x16x32_bf16 v[108:111], v[90:93], v[224:227], v[108:111]
	v_mfma_f32_16x16x32_bf16 v[104:107], v[168:171], v[224:227], v[104:107]
	v_mfma_f32_16x16x32_bf16 v[76:79], v[90:93], v[242:245], v[76:79]
	v_mfma_f32_16x16x32_bf16 v[72:75], v[168:171], v[242:245], v[72:75]
	s_setprio 0
	s_setprio 1
	v_mfma_f32_16x16x32_bf16 v[132:135], v[172:175], v[188:191], v[132:135]
	v_mfma_f32_16x16x32_bf16 v[128:131], v[180:183], v[188:191], v[128:131]
	v_mfma_f32_16x16x32_bf16 v[116:119], v[172:175], v[212:215], v[116:119]
	v_mfma_f32_16x16x32_bf16 v[112:115], v[180:183], v[212:215], v[112:115]
	v_mfma_f32_16x16x32_bf16 v[98:101], v[172:175], v[220:223], v[100:103]
	v_mfma_f32_16x16x32_bf16 v[94:97], v[180:183], v[220:223], v[94:97]
	v_mfma_f32_16x16x32_bf16 v[68:71], v[172:175], v[228:231], v[68:71]
	v_mfma_f32_16x16x32_bf16 v[64:67], v[180:183], v[228:231], v[64:67]
	v_mfma_f32_16x16x32_bf16 v[132:135], v[176:179], v[208:211], v[132:135]
	v_mfma_f32_16x16x32_bf16 v[128:131], v[184:187], v[208:211], v[128:131]
	v_mfma_f32_16x16x32_bf16 v[116:119], v[176:179], v[216:219], v[116:119]
	v_mfma_f32_16x16x32_bf16 v[112:115], v[184:187], v[216:219], v[112:115]
	v_mfma_f32_16x16x32_bf16 v[100:103], v[176:179], v[224:227], v[98:101]
	v_mfma_f32_16x16x32_bf16 v[96:99], v[184:187], v[224:227], v[94:97]
	v_mfma_f32_16x16x32_bf16 v[68:71], v[176:179], v[242:245], v[68:71]
	v_mfma_f32_16x16x32_bf16 v[64:67], v[184:187], v[242:245], v[64:67]
	s_setprio 0
	s_barrier
; #define PG8_STAGE(bufoff, gbase, voff) do { _Pragma("unroll") for (int _i = 0; _i < 2; ++_i) \
;         __builtin_amdgcn_global_load_lds((const unsigned*)((const char*)(gbase) + (voff)[_i]), (PG8_LAS unsigned*)(lds + (bufoff) + ldsw + _i * (8 * USTR)), 16, 0, 0); } while (0)
; #define PG8_LDA(dst, b, h) do { _Pragma("unroll") for (int m = 0; m < 4; ++m) _Pragma("unroll") for (int k = 0; k < 2; ++k) dst[m][k] = *(const PG8_LAS bf16x8*)(lds + PG8_SA(b, h) + aoff + m * (2 * USTR) + k * 64); } while (0)
; #define PG8_MMA(ai, bj, At, Bt) do { __builtin_amdgcn_s_setprio(1); _Pragma("unroll") for (int m = 0; m < 4; ++m) _Pragma("unroll") for (int n = 0; n < 2; ++n) _Pragma("unroll") for (int k = 0; k < 2; ++k) \
;         acc[ai][bj][m][n] = __builtin_amdgcn_mfma_f32_16x16x32_bf16(Bt[n][k], At[m][k], acc[ai][bj][m][n], 0, 0, 0); __builtin_amdgcn_s_setprio(0); } while (0)
; #define PG8_WAIT_V(n) asm volatile("s_waitcnt vmcnt(" #n ")" ::: "memory")
; #define PG8_WAIT_L(n) asm volatile("s_waitcnt lgkmcnt(" #n ")" ::: "memory")
; #define PG8_BAR __builtin_amdgcn_s_barrier()
; #define PG8_SCHED __builtin_amdgcn_sched_barrier(0)
; template <class Epi, class Sched, bool ALIGN_EPI, bool SP2>
; __device__ __forceinline__ void gemm_phase(PG8_LAS unsigned char* lds, const Gemm g, const Sched& S, const Epi& E, int wid) {
;     ...
;         for (int t = 0; t < nt; t += 2) {
;             const bool last = (t == nt - 2);
;             const char* a1 = cA + (size_t)(t + 1) * kstep;
;             const char* a2 = last ? nA : cA + (size_t)(t + 2) * kstep; const char* b2 = last ? nB : cB + (size_t)(t + 2) * kstep;
;     ...
;             PG8_LDA(At, 1, 1); PG8_STAGE(PG8_SB(1, 0), b3, voffB); PG8_STAGE(PG8_SB(1, 1), b3 + hstepB, voffB); PG8_STAGE(PG8_SA(1, 0), a3, voffA);
;             PG8_WAIT_V(8); PG8_WAIT_L(0); PG8_BAR; PG8_MMA(1, 0, At, B0); PG8_MMA(1, 1, At, B1); PG8_BAR; PG8_SCHED;
	s_add_i32 s70, s77, s33
	v_lshl_add_u64 v[94:95], v[158:159], 0, s[6:7]
	s_mov_b32 m0, s70
	ds_read_b128 v[188:191], v163 offset:52224
	ds_read_b128 v[208:211], v163 offset:52288
	ds_read_b128 v[212:215], v163 offset:54400
	ds_read_b128 v[216:219], v163 offset:54464
	ds_read_b128 v[220:223], v163 offset:56576
	ds_read_b128 v[224:227], v163 offset:56640
	ds_read_b128 v[228:231], v163 offset:58752
	ds_read_b128 v[242:245], v163 offset:58816
	global_load_lds_dwordx4 v[94:95], off
	s_add_i32 m0, s70, 0x2200
	s_add_u32 s68, s68, 0x40080
	v_lshl_add_u64 v[94:95], v[198:199], 0, s[6:7]
	s_addc_u32 s69, s69, 0
	s_add_i32 s70, s78, s33
	global_load_lds_dwordx4 v[94:95], off
	v_lshl_add_u64 v[94:95], s[68:69], 0, v[192:193]
	s_mov_b32 m0, s70
	s_nop 0
	global_load_lds_dwordx4 v[94:95], off
	v_lshl_add_u64 v[94:95], s[68:69], 0, v[144:145]
	s_add_i32 m0, s70, 0x2200
	s_nop 0
	global_load_lds_dwordx4 v[94:95], off
	v_lshl_add_u64 v[94:95], v[200:201], 0, s[6:7]
	s_mov_b32 m0, s56
	s_nop 0
	global_load_lds_dwordx4 v[94:95], off
	v_lshl_add_u64 v[94:95], v[232:233], 0, s[6:7]
	s_mov_b32 m0, s57
	s_nop 0
	global_load_lds_dwordx4 v[94:95], off
	s_add_i32 s76, s76, 2
	s_add_u32 s38, s38, 0x100
	s_addc_u32 s39, s39, 0
	s_add_u32 s74, s74, 0x100
	s_addc_u32 s75, s75, 0
	s_waitcnt vmcnt(8)
	s_waitcnt lgkmcnt(0)
	s_barrier
	s_setprio 1
	s_waitcnt lgkmcnt(0)
	v_mfma_f32_16x16x32_bf16 v[60:63], v[86:89], v[188:191], v[60:63]
	v_mfma_f32_16x16x32_bf16 v[56:59], v[164:167], v[188:191], v[56:59]
	v_mfma_f32_16x16x32_bf16 v[44:47], v[86:89], v[212:215], v[44:47]
	v_mfma_f32_16x16x32_bf16 v[40:43], v[164:167], v[212:215], v[40:43]
	v_mfma_f32_16x16x32_bf16 v[28:31], v[86:89], v[220:223], v[28:31]
	v_mfma_f32_16x16x32_bf16 v[24:27], v[164:167], v[220:223], v[24:27]
	v_mfma_f32_16x16x32_bf16 v[12:15], v[86:89], v[228:231], v[12:15]
	v_mfma_f32_16x16x32_bf16 v[8:11], v[164:167], v[228:231], v[8:11]
	v_mfma_f32_16x16x32_bf16 v[60:63], v[90:93], v[208:211], v[60:63]
	v_mfma_f32_16x16x32_bf16 v[56:59], v[168:171], v[208:211], v[56:59]
	v_mfma_f32_16x16x32_bf16 v[44:47], v[90:93], v[216:219], v[44:47]
	v_mfma_f32_16x16x32_bf16 v[40:43], v[168:171], v[216:219], v[40:43]
	v_mfma_f32_16x16x32_bf16 v[28:31], v[90:93], v[224:227], v[28:31]
	v_mfma_f32_16x16x32_bf16 v[24:27], v[168:171], v[224:227], v[24:27]
	v_mfma_f32_16x16x32_bf16 v[12:15], v[90:93], v[242:245], v[12:15]
	v_mfma_f32_16x16x32_bf16 v[8:11], v[168:171], v[242:245], v[8:11]
	s_setprio 0
	s_setprio 1
	v_mfma_f32_16x16x32_bf16 v[52:55], v[172:175], v[188:191], v[52:55]
	v_mfma_f32_16x16x32_bf16 v[48:51], v[180:183], v[188:191], v[48:51]
	v_mfma_f32_16x16x32_bf16 v[36:39], v[172:175], v[212:215], v[36:39]
	v_mfma_f32_16x16x32_bf16 v[32:35], v[180:183], v[212:215], v[32:35]
	v_mfma_f32_16x16x32_bf16 v[20:23], v[172:175], v[220:223], v[20:23]
	v_mfma_f32_16x16x32_bf16 v[16:19], v[180:183], v[220:223], v[16:19]
	v_mfma_f32_16x16x32_bf16 v[4:7], v[172:175], v[228:231], v[4:7]
	v_mfma_f32_16x16x32_bf16 v[0:3], v[180:183], v[228:231], v[0:3]
	v_mfma_f32_16x16x32_bf16 v[52:55], v[176:179], v[208:211], v[52:55]
	v_mfma_f32_16x16x32_bf16 v[48:51], v[184:187], v[208:211], v[48:51]
	v_mfma_f32_16x16x32_bf16 v[36:39], v[176:179], v[216:219], v[36:39]
	v_mfma_f32_16x16x32_bf16 v[32:35], v[184:187], v[216:219], v[32:35]
	v_mfma_f32_16x16x32_bf16 v[20:23], v[176:179], v[224:227], v[20:23]
	v_mfma_f32_16x16x32_bf16 v[16:19], v[184:187], v[224:227], v[16:19]
	v_mfma_f32_16x16x32_bf16 v[4:7], v[176:179], v[242:245], v[4:7]
	v_mfma_f32_16x16x32_bf16 v[0:3], v[184:187], v[242:245], v[0:3]
	s_setprio 0
	s_barrier
	s_cmp_lt_u32 s76, 12
	s_cbranch_scc0 .Ledge_slow_up
	s_mov_b64 s[68:69], 0
	s_branch .LBB0_373
.Ledge_slow_up:
	s_cmp_gt_u32 s76, 13
	s_cbranch_scc1 .LBB0_377

; #define PG8_STAGE(bufoff, gbase, voff) do { _Pragma("unroll") for (int _i = 0; _i < 2; ++_i) \
;         __builtin_amdgcn_global_load_lds((const unsigned*)((const char*)(gbase) + (voff)[_i]), (PG8_LAS unsigned*)(lds + (bufoff) + ldsw + _i * (8 * USTR)), 16, 0, 0); } while (0)
; #define PG8_LDA(dst, b, h) do { _Pragma("unroll") for (int m = 0; m < 4; ++m) _Pragma("unroll") for (int k = 0; k < 2; ++k) dst[m][k] = *(const PG8_LAS bf16x8*)(lds + PG8_SA(b, h) + aoff + m * (2 * USTR) + k * 64); } while (0)
; #define PG8_LDB(dst, b, h) do { _Pragma("unroll") for (int n = 0; n < 2; ++n) _Pragma("unroll") for (int k = 0; k < 2; ++k) dst[n][k] = *(const PG8_LAS bf16x8*)(lds + PG8_SB(b, h) + boff + n * (2 * USTR) + k * 64); } while (0)
; #define PG8_MMA(ai, bj, At, Bt) do { __builtin_amdgcn_s_setprio(1); _Pragma("unroll") for (int m = 0; m < 4; ++m) _Pragma("unroll") for (int n = 0; n < 2; ++n) _Pragma("unroll") for (int k = 0; k < 2; ++k) \
;         acc[ai][bj][m][n] = __builtin_amdgcn_mfma_f32_16x16x32_bf16(Bt[n][k], At[m][k], acc[ai][bj][m][n], 0, 0, 0); __builtin_amdgcn_s_setprio(0); } while (0)
; #define PG8_WAIT_V(n) asm volatile("s_waitcnt vmcnt(" #n ")" ::: "memory")
; #define PG8_WAIT_L(n) asm volatile("s_waitcnt lgkmcnt(" #n ")" ::: "memory")
; #define PG8_BAR __builtin_amdgcn_s_barrier()
; #define PG8_SCHED __builtin_amdgcn_sched_barrier(0)
; template <class Epi, class Sched, bool ALIGN_EPI, bool SP2>
; __device__ __forceinline__ void gemm_phase(PG8_LAS unsigned char* lds, const Gemm g, const Sched& S, const Epi& E, int wid) {
;     ...
;             PG8_LDB(B0, 0, 0); PG8_LDB(B1, 0, 1); PG8_SCHED; PG8_LDA(At, 0, 0); PG8_STAGE(PG8_SA(1, 1), a1 + hstepA, voffA);
;             PG8_WAIT_V(8); PG8_WAIT_L(0); PG8_BAR; PG8_MMA(0, 0, At, B0); PG8_MMA(0, 1, At, B1); PG8_BAR; PG8_SCHED;
;             PG8_LDA(At, 0, 1); PG8_STAGE(PG8_SB(0, 0), b2, voffB); PG8_STAGE(PG8_SB(0, 1), b2 + hstepB, voffB); PG8_STAGE(PG8_SA(0, 0), a2, voffA);
;             PG8_WAIT_V(8); PG8_WAIT_L(0); PG8_BAR; PG8_MMA(1, 0, At, B0); PG8_MMA(1, 1, At, B1); PG8_BAR; PG8_SCHED;
.LBB0_393:
	v_add_u32_e32 v30, 0x11000, v197
	s_add_i32 s73, 0, 0x11000
	s_add_i32 vcc_lo, 0, 0x15400
	ds_read_b128 v[22:25], v30
	ds_read_b128 v[26:29], v30 offset:64
	ds_read_b128 v[158:161], v30 offset:2176
	ds_read_b128 v[162:165], v30 offset:2240
	v_add_u32_e32 v30, vcc_lo, v197
	ds_read_b128 v[166:169], v30
	ds_read_b128 v[170:173], v30 offset:64
	ds_read_b128 v[174:177], v30 offset:2176
	ds_read_b128 v[178:181], v30 offset:2240
	v_lshl_add_u64 v[30:31], s[38:39], 0, v[154:155]
	s_add_i32 m0, s95, 0xcc00
	ds_read_b128 v[182:185], v210
	ds_read_b128 v[186:189], v210 offset:64
	ds_read_b128 v[212:215], v210 offset:2176
	ds_read_b128 v[216:219], v210 offset:2240
	ds_read_b128 v[220:223], v210 offset:4352
	ds_read_b128 v[224:227], v210 offset:4416
	ds_read_b128 v[228:231], v210 offset:6528
	ds_read_b128 v[242:245], v210 offset:6592
	global_load_lds_dwordx4 v[30:31], off
	v_lshl_add_u64 v[30:31], s[38:39], 0, v[156:157]
	s_add_i32 m0, s95, 0xee00
	s_nop 0
	global_load_lds_dwordx4 v[30:31], off
	s_add_u32 s42, s38, 0xfffc0080
	s_addc_u32 s43, s39, -1
	s_and_b64 s[40:41], s[40:41], exec
	s_cselect_b32 s43, s10, s43
	s_cselect_b32 s42, s44, s42
	s_cselect_b32 s41, s45, s70
	s_cselect_b32 s40, s69, s23
	s_waitcnt vmcnt(8)
	s_waitcnt lgkmcnt(0)
	s_barrier
	s_setprio 1
	s_waitcnt lgkmcnt(0)
	v_mfma_f32_16x16x32_bf16 v[140:143], v[22:25], v[182:185], v[140:143]
	v_mfma_f32_16x16x32_bf16 v[136:139], v[158:161], v[182:185], v[136:139]
	v_mfma_f32_16x16x32_bf16 v[124:127], v[22:25], v[212:215], v[124:127]
	v_mfma_f32_16x16x32_bf16 v[120:123], v[158:161], v[212:215], v[120:123]
	v_mfma_f32_16x16x32_bf16 v[108:111], v[22:25], v[220:223], v[108:111]
	v_mfma_f32_16x16x32_bf16 v[104:107], v[158:161], v[220:223], v[104:107]
	v_mfma_f32_16x16x32_bf16 v[92:95], v[22:25], v[228:231], v[92:95]
	v_mfma_f32_16x16x32_bf16 v[88:91], v[158:161], v[228:231], v[88:91]
	v_mfma_f32_16x16x32_bf16 v[140:143], v[26:29], v[186:189], v[140:143]
	v_mfma_f32_16x16x32_bf16 v[136:139], v[162:165], v[186:189], v[136:139]
	v_mfma_f32_16x16x32_bf16 v[124:127], v[26:29], v[216:219], v[124:127]
	v_mfma_f32_16x16x32_bf16 v[120:123], v[162:165], v[216:219], v[120:123]
	v_mfma_f32_16x16x32_bf16 v[108:111], v[26:29], v[224:227], v[108:111]
	v_mfma_f32_16x16x32_bf16 v[104:107], v[162:165], v[224:227], v[104:107]
	v_mfma_f32_16x16x32_bf16 v[92:95], v[26:29], v[242:245], v[92:95]
	v_mfma_f32_16x16x32_bf16 v[88:91], v[162:165], v[242:245], v[88:91]
	s_setprio 0
	s_setprio 1
	v_mfma_f32_16x16x32_bf16 v[132:135], v[166:169], v[182:185], v[132:135]
	v_mfma_f32_16x16x32_bf16 v[128:131], v[174:177], v[182:185], v[128:131]
	v_mfma_f32_16x16x32_bf16 v[116:119], v[166:169], v[212:215], v[116:119]
	v_mfma_f32_16x16x32_bf16 v[112:115], v[174:177], v[212:215], v[112:115]
	v_mfma_f32_16x16x32_bf16 v[100:103], v[166:169], v[220:223], v[100:103]
	v_mfma_f32_16x16x32_bf16 v[96:99], v[174:177], v[220:223], v[96:99]
	v_mfma_f32_16x16x32_bf16 v[84:87], v[166:169], v[228:231], v[84:87]
	v_mfma_f32_16x16x32_bf16 v[80:83], v[174:177], v[228:231], v[80:83]
	v_mfma_f32_16x16x32_bf16 v[132:135], v[170:173], v[186:189], v[132:135]
	v_mfma_f32_16x16x32_bf16 v[128:131], v[178:181], v[186:189], v[128:131]
	v_mfma_f32_16x16x32_bf16 v[116:119], v[170:173], v[216:219], v[116:119]
	v_mfma_f32_16x16x32_bf16 v[112:115], v[178:181], v[216:219], v[112:115]
	v_mfma_f32_16x16x32_bf16 v[100:103], v[170:173], v[224:227], v[100:103]
	v_mfma_f32_16x16x32_bf16 v[96:99], v[178:181], v[224:227], v[96:99]
	v_mfma_f32_16x16x32_bf16 v[84:87], v[170:173], v[242:245], v[84:87]
	v_mfma_f32_16x16x32_bf16 v[80:83], v[178:181], v[242:245], v[80:83]
	s_setprio 0
	s_barrier
	s_add_i32 s73, s73, s33
	v_lshl_add_u64 v[190:191], s[40:41], 0, v[192:193]
	s_mov_b32 m0, s73
	ds_read_b128 v[182:185], v210 offset:17408
	ds_read_b128 v[186:189], v210 offset:17472
	ds_read_b128 v[212:215], v210 offset:19584
	ds_read_b128 v[216:219], v210 offset:19648
	ds_read_b128 v[220:223], v210 offset:21760
	ds_read_b128 v[224:227], v210 offset:21824
	ds_read_b128 v[228:231], v210 offset:23936
	ds_read_b128 v[242:245], v210 offset:24000
	global_load_lds_dwordx4 v[190:191], off
	s_add_i32 m0, s73, 0x2200
	s_add_u32 s76, s40, 0x40000
	v_lshl_add_u64 v[198:199], s[40:41], 0, v[146:147]
	s_addc_u32 s77, s41, 0
	s_add_i32 s73, vcc_lo, s33
	global_load_lds_dwordx4 v[198:199], off
	v_lshl_add_u64 v[30:31], s[76:77], 0, v[192:193]
	s_mov_b32 m0, s73
	v_lshl_add_u64 v[200:201], s[42:43], 0, v[150:151]
	global_load_lds_dwordx4 v[30:31], off
	v_lshl_add_u64 v[30:31], s[76:77], 0, v[146:147]
	s_add_i32 m0, s73, 0x2200
	v_lshl_add_u64 v[208:209], s[42:43], 0, v[148:149]
	global_load_lds_dwordx4 v[30:31], off
	s_mov_b32 m0, s95
	s_nop 0
	global_load_lds_dwordx4 v[200:201], off
	s_mov_b32 m0, s5
	s_nop 0
	global_load_lds_dwordx4 v[208:209], off
	s_waitcnt vmcnt(8)
	s_waitcnt lgkmcnt(0)
	s_barrier
; #define PG8_STAGE(bufoff, gbase, voff) do { _Pragma("unroll") for (int _i = 0; _i < 2; ++_i) \
;         __builtin_amdgcn_global_load_lds((const unsigned*)((const char*)(gbase) + (voff)[_i]), (PG8_LAS unsigned*)(lds + (bufoff) + ldsw + _i * (8 * USTR)), 16, 0, 0); } while (0)
; #define PG8_LDA(dst, b, h) do { _Pragma("unroll") for (int m = 0; m < 4; ++m) _Pragma("unroll") for (int k = 0; k < 2; ++k) dst[m][k] = *(const PG8_LAS bf16x8*)(lds + PG8_SA(b, h) + aoff + m * (2 * USTR) + k * 64); } while (0)
; #define PG8_LDB(dst, b, h) do { _Pragma("unroll") for (int n = 0; n < 2; ++n) _Pragma("unroll") for (int k = 0; k < 2; ++k) dst[n][k] = *(const PG8_LAS bf16x8*)(lds + PG8_SB(b, h) + boff + n * (2 * USTR) + k * 64); } while (0)
; #define PG8_MMA(ai, bj, At, Bt) do { __builtin_amdgcn_s_setprio(1); _Pragma("unroll") for (int m = 0; m < 4; ++m) _Pragma("unroll") for (int n = 0; n < 2; ++n) _Pragma("unroll") for (int k = 0; k < 2; ++k) \
;         acc[ai][bj][m][n] = __builtin_amdgcn_mfma_f32_16x16x32_bf16(Bt[n][k], At[m][k], acc[ai][bj][m][n], 0, 0, 0); __builtin_amdgcn_s_setprio(0); } while (0)
; #define PG8_WAIT_V(n) asm volatile("s_waitcnt vmcnt(" #n ")" ::: "memory")
; #define PG8_WAIT_L(n) asm volatile("s_waitcnt lgkmcnt(" #n ")" ::: "memory")
; #define PG8_BAR __builtin_amdgcn_s_barrier()
; #define PG8_SCHED __builtin_amdgcn_sched_barrier(0)
; template <class Epi, class Sched, bool ALIGN_EPI, bool SP2>
; __device__ __forceinline__ void gemm_phase(PG8_LAS unsigned char* lds, const Gemm g, const Sched& S, const Epi& E, int wid) {
;     ...
;             PG8_WAIT_V(8); PG8_WAIT_L(0); PG8_BAR; PG8_MMA(1, 0, At, B0); PG8_MMA(1, 1, At, B1); PG8_BAR; PG8_SCHED;
;             PG8_LDB(B0, 1, 0); PG8_LDB(B1, 1, 1); PG8_SCHED; PG8_LDA(At, 1, 0); PG8_STAGE(PG8_SA(0, 1), a2 + hstepA, voffA);
;             PG8_WAIT_V(8); PG8_WAIT_L(0); PG8_BAR; PG8_MMA(0, 0, At, B0); PG8_MMA(0, 1, At, B1); PG8_BAR; PG8_SCHED;
	s_setprio 1
	s_waitcnt lgkmcnt(0)
	v_mfma_f32_16x16x32_bf16 v[76:79], v[22:25], v[182:185], v[76:79]
	v_mfma_f32_16x16x32_bf16 v[72:75], v[158:161], v[182:185], v[72:75]
	v_mfma_f32_16x16x32_bf16 v[60:63], v[22:25], v[212:215], v[60:63]
	v_mfma_f32_16x16x32_bf16 v[56:59], v[158:161], v[212:215], v[56:59]
	v_mfma_f32_16x16x32_bf16 v[44:47], v[22:25], v[220:223], v[44:47]
	v_mfma_f32_16x16x32_bf16 v[40:43], v[158:161], v[220:223], v[40:43]
	v_mfma_f32_16x16x32_bf16 v[12:15], v[22:25], v[228:231], v[12:15]
	v_mfma_f32_16x16x32_bf16 v[8:11], v[158:161], v[228:231], v[8:11]
	v_mfma_f32_16x16x32_bf16 v[76:79], v[26:29], v[186:189], v[76:79]
	v_mfma_f32_16x16x32_bf16 v[72:75], v[162:165], v[186:189], v[72:75]
	v_mfma_f32_16x16x32_bf16 v[60:63], v[26:29], v[216:219], v[60:63]
	v_mfma_f32_16x16x32_bf16 v[56:59], v[162:165], v[216:219], v[56:59]
	v_mfma_f32_16x16x32_bf16 v[44:47], v[26:29], v[224:227], v[44:47]
	v_mfma_f32_16x16x32_bf16 v[40:43], v[162:165], v[224:227], v[40:43]
	v_mfma_f32_16x16x32_bf16 v[12:15], v[26:29], v[242:245], v[12:15]
	v_mfma_f32_16x16x32_bf16 v[8:11], v[162:165], v[242:245], v[8:11]
	s_setprio 0
	s_setprio 1
	v_mfma_f32_16x16x32_bf16 v[52:55], v[166:169], v[212:215], v[52:55]
	v_mfma_f32_16x16x32_bf16 v[48:51], v[174:177], v[212:215], v[48:51]
	v_mfma_f32_16x16x32_bf16 v[36:39], v[166:169], v[220:223], v[36:39]
	v_mfma_f32_16x16x32_bf16 v[30:33], v[174:177], v[220:223], v[32:35]
	v_mfma_f32_16x16x32_bf16 v[4:7], v[166:169], v[228:231], v[4:7]
	v_mfma_f32_16x16x32_bf16 v[0:3], v[174:177], v[228:231], v[0:3]
	v_mfma_f32_16x16x32_bf16 v[22:25], v[166:169], v[182:185], v[68:71]
	v_mfma_f32_16x16x32_bf16 v[26:29], v[174:177], v[182:185], v[64:67]
	v_mfma_f32_16x16x32_bf16 v[52:55], v[170:173], v[216:219], v[52:55]
	v_mfma_f32_16x16x32_bf16 v[48:51], v[178:181], v[216:219], v[48:51]
	v_mfma_f32_16x16x32_bf16 v[36:39], v[170:173], v[224:227], v[36:39]
	v_mfma_f32_16x16x32_bf16 v[30:33], v[178:181], v[224:227], v[30:33]
	v_mfma_f32_16x16x32_bf16 v[4:7], v[170:173], v[242:245], v[4:7]
	v_mfma_f32_16x16x32_bf16 v[0:3], v[178:181], v[242:245], v[0:3]
	v_mfma_f32_16x16x32_bf16 v[22:25], v[170:173], v[186:189], v[22:25]
	v_mfma_f32_16x16x32_bf16 v[26:29], v[178:181], v[186:189], v[26:29]
	s_setprio 0
	s_barrier
	v_add_u32_e32 v34, 0x19800, v197
	ds_read_b128 v[64:67], v34
	ds_read_b128 v[68:71], v34 offset:64
	ds_read_b128 v[158:161], v34 offset:2176
	ds_read_b128 v[162:165], v34 offset:2240
	v_add_u32_e32 v34, 0x1dc00, v197
	ds_read_b128 v[166:169], v34
	ds_read_b128 v[170:173], v34 offset:64
	ds_read_b128 v[174:177], v34 offset:2176
	ds_read_b128 v[178:181], v34 offset:2240
	s_add_i32 s73, 0, 0x19800
	s_add_i32 s76, 0, 0x1dc00
	s_add_u32 s42, s42, 0x40000
	s_addc_u32 s43, s43, 0
	s_mov_b32 m0, s56
	v_lshl_add_u64 v[34:35], s[42:43], 0, v[150:151]
	ds_read_b128 v[182:185], v210 offset:34816
	ds_read_b128 v[186:189], v210 offset:34880
	ds_read_b128 v[212:215], v210 offset:36992
	ds_read_b128 v[216:219], v210 offset:37056
	ds_read_b128 v[220:223], v210 offset:39168
	ds_read_b128 v[224:227], v210 offset:39232
	ds_read_b128 v[228:231], v210 offset:41344
	ds_read_b128 v[242:245], v210 offset:41408
	global_load_lds_dwordx4 v[34:35], off
	v_lshl_add_u64 v[34:35], s[42:43], 0, v[148:149]
	s_mov_b32 m0, s57
	s_nop 0
	global_load_lds_dwordx4 v[34:35], off
	s_waitcnt vmcnt(8)
	s_waitcnt lgkmcnt(0)
	s_barrier
	s_setprio 1
	s_waitcnt lgkmcnt(0)
	v_mfma_f32_16x16x32_bf16 v[140:143], v[64:67], v[182:185], v[140:143]
	v_mfma_f32_16x16x32_bf16 v[136:139], v[158:161], v[182:185], v[136:139]
	v_mfma_f32_16x16x32_bf16 v[124:127], v[64:67], v[212:215], v[124:127]
	v_mfma_f32_16x16x32_bf16 v[120:123], v[158:161], v[212:215], v[120:123]
	v_mfma_f32_16x16x32_bf16 v[108:111], v[64:67], v[220:223], v[108:111]
	v_mfma_f32_16x16x32_bf16 v[104:107], v[158:161], v[220:223], v[104:107]
	v_mfma_f32_16x16x32_bf16 v[92:95], v[64:67], v[228:231], v[92:95]
	v_mfma_f32_16x16x32_bf16 v[88:91], v[158:161], v[228:231], v[88:91]
	v_mfma_f32_16x16x32_bf16 v[140:143], v[68:71], v[186:189], v[140:143]
	v_mfma_f32_16x16x32_bf16 v[136:139], v[162:165], v[186:189], v[136:139]
	v_mfma_f32_16x16x32_bf16 v[124:127], v[68:71], v[216:219], v[124:127]
	v_mfma_f32_16x16x32_bf16 v[120:123], v[162:165], v[216:219], v[120:123]
	v_mfma_f32_16x16x32_bf16 v[108:111], v[68:71], v[224:227], v[108:111]
	v_mfma_f32_16x16x32_bf16 v[104:107], v[162:165], v[224:227], v[104:107]
	v_mfma_f32_16x16x32_bf16 v[92:95], v[68:71], v[242:245], v[92:95]
	v_mfma_f32_16x16x32_bf16 v[88:91], v[162:165], v[242:245], v[88:91]
	s_setprio 0
	s_setprio 1
	v_mfma_f32_16x16x32_bf16 v[132:135], v[166:169], v[182:185], v[132:135]
	v_mfma_f32_16x16x32_bf16 v[128:131], v[174:177], v[182:185], v[128:131]
	v_mfma_f32_16x16x32_bf16 v[116:119], v[166:169], v[212:215], v[116:119]
	v_mfma_f32_16x16x32_bf16 v[112:115], v[174:177], v[212:215], v[112:115]
	v_mfma_f32_16x16x32_bf16 v[100:103], v[166:169], v[220:223], v[100:103]
	v_mfma_f32_16x16x32_bf16 v[96:99], v[174:177], v[220:223], v[96:99]
	v_mfma_f32_16x16x32_bf16 v[84:87], v[166:169], v[228:231], v[84:87]
	v_mfma_f32_16x16x32_bf16 v[80:83], v[174:177], v[228:231], v[80:83]
	v_mfma_f32_16x16x32_bf16 v[132:135], v[170:173], v[186:189], v[132:135]
	v_mfma_f32_16x16x32_bf16 v[128:131], v[178:181], v[186:189], v[128:131]
	v_mfma_f32_16x16x32_bf16 v[116:119], v[170:173], v[216:219], v[116:119]
	v_mfma_f32_16x16x32_bf16 v[112:115], v[178:181], v[216:219], v[112:115]
	v_mfma_f32_16x16x32_bf16 v[100:103], v[170:173], v[224:227], v[100:103]
	v_mfma_f32_16x16x32_bf16 v[96:99], v[178:181], v[224:227], v[96:99]
	v_mfma_f32_16x16x32_bf16 v[84:87], v[170:173], v[242:245], v[84:87]
	v_mfma_f32_16x16x32_bf16 v[80:83], v[178:181], v[242:245], v[80:83]
	s_setprio 0
	s_barrier
; #define PG8_STAGE(bufoff, gbase, voff) do { _Pragma("unroll") for (int _i = 0; _i < 2; ++_i) \
;         __builtin_amdgcn_global_load_lds((const unsigned*)((const char*)(gbase) + (voff)[_i]), (PG8_LAS unsigned*)(lds + (bufoff) + ldsw + _i * (8 * USTR)), 16, 0, 0); } while (0)
; #define PG8_LDA(dst, b, h) do { _Pragma("unroll") for (int m = 0; m < 4; ++m) _Pragma("unroll") for (int k = 0; k < 2; ++k) dst[m][k] = *(const PG8_LAS bf16x8*)(lds + PG8_SA(b, h) + aoff + m * (2 * USTR) + k * 64); } while (0)
; #define PG8_MMA(ai, bj, At, Bt) do { __builtin_amdgcn_s_setprio(1); _Pragma("unroll") for (int m = 0; m < 4; ++m) _Pragma("unroll") for (int n = 0; n < 2; ++n) _Pragma("unroll") for (int k = 0; k < 2; ++k) \
;         acc[ai][bj][m][n] = __builtin_amdgcn_mfma_f32_16x16x32_bf16(Bt[n][k], At[m][k], acc[ai][bj][m][n], 0, 0, 0); __builtin_amdgcn_s_setprio(0); } while (0)
; #define PG8_WAIT_V(n) asm volatile("s_waitcnt vmcnt(" #n ")" ::: "memory")
; #define PG8_WAIT_L(n) asm volatile("s_waitcnt lgkmcnt(" #n ")" ::: "memory")
; #define PG8_BAR __builtin_amdgcn_s_barrier()
; #define PG8_SCHED __builtin_amdgcn_sched_barrier(0)
; template <class Epi, class Sched, bool ALIGN_EPI, bool SP2>
; __device__ __forceinline__ void gemm_phase(PG8_LAS unsigned char* lds, const Gemm g, const Sched& S, const Epi& E, int wid) {
;     ...
;         for (int t = 0; t < nt; t += 2) {
;             const bool last = (t == nt - 2);
;             const char* a1 = cA + (size_t)(t + 1) * kstep;
;             const char* a2 = last ? nA : cA + (size_t)(t + 2) * kstep; const char* b2 = last ? nB : cB + (size_t)(t + 2) * kstep;
;     ...
;             PG8_LDA(At, 1, 1); PG8_STAGE(PG8_SB(1, 0), b3, voffB); PG8_STAGE(PG8_SB(1, 1), b3 + hstepB, voffB); PG8_STAGE(PG8_SA(1, 0), a3, voffA);
;             PG8_WAIT_V(8); PG8_WAIT_L(0); PG8_BAR; PG8_MMA(1, 0, At, B0); PG8_MMA(1, 1, At, B1); PG8_BAR; PG8_SCHED;
	s_add_i32 s42, s73, s33
	v_lshl_add_u64 v[34:35], v[190:191], 0, s[6:7]
	s_mov_b32 m0, s42
	ds_read_b128 v[182:185], v210 offset:52224
	ds_read_b128 v[186:189], v210 offset:52288
	ds_read_b128 v[212:215], v210 offset:54400
	ds_read_b128 v[216:219], v210 offset:54464
	ds_read_b128 v[220:223], v210 offset:56576
	ds_read_b128 v[224:227], v210 offset:56640
	ds_read_b128 v[228:231], v210 offset:58752
	ds_read_b128 v[242:245], v210 offset:58816
	global_load_lds_dwordx4 v[34:35], off
	s_add_i32 m0, s42, 0x2200
	s_add_u32 s40, s40, 0x40080
	v_lshl_add_u64 v[34:35], v[198:199], 0, s[6:7]
	s_addc_u32 s41, s41, 0
	s_add_i32 s42, s76, s33
	global_load_lds_dwordx4 v[34:35], off
	v_lshl_add_u64 v[34:35], s[40:41], 0, v[192:193]
	s_mov_b32 m0, s42
	s_nop 0
	global_load_lds_dwordx4 v[34:35], off
	v_lshl_add_u64 v[34:35], s[40:41], 0, v[146:147]
	s_add_i32 m0, s42, 0x2200
	s_nop 0
	global_load_lds_dwordx4 v[34:35], off
	v_lshl_add_u64 v[34:35], v[200:201], 0, s[6:7]
	s_mov_b32 m0, s29
	s_nop 0
	global_load_lds_dwordx4 v[34:35], off
	v_lshl_add_u64 v[34:35], v[208:209], 0, s[6:7]
	s_mov_b32 m0, s0
	s_nop 0
	global_load_lds_dwordx4 v[34:35], off
	s_add_i32 s71, s71, 2
	s_add_u32 s38, s38, 0x100
	s_addc_u32 s39, s39, 0
	s_add_u32 s23, s23, 0x100
	s_addc_u32 s70, s70, 0
	s_waitcnt vmcnt(8)
	s_waitcnt lgkmcnt(0)
	s_barrier
	s_setprio 1
	s_waitcnt lgkmcnt(0)
	v_mfma_f32_16x16x32_bf16 v[76:79], v[64:67], v[182:185], v[76:79]
	v_mfma_f32_16x16x32_bf16 v[72:75], v[158:161], v[182:185], v[72:75]
	v_mfma_f32_16x16x32_bf16 v[60:63], v[64:67], v[212:215], v[60:63]
	v_mfma_f32_16x16x32_bf16 v[56:59], v[158:161], v[212:215], v[56:59]
	v_mfma_f32_16x16x32_bf16 v[44:47], v[64:67], v[220:223], v[44:47]
	v_mfma_f32_16x16x32_bf16 v[40:43], v[158:161], v[220:223], v[40:43]
	v_mfma_f32_16x16x32_bf16 v[12:15], v[64:67], v[228:231], v[12:15]
	v_mfma_f32_16x16x32_bf16 v[8:11], v[158:161], v[228:231], v[8:11]
	v_mfma_f32_16x16x32_bf16 v[76:79], v[68:71], v[186:189], v[76:79]
	v_mfma_f32_16x16x32_bf16 v[72:75], v[162:165], v[186:189], v[72:75]
	v_mfma_f32_16x16x32_bf16 v[60:63], v[68:71], v[216:219], v[60:63]
	v_mfma_f32_16x16x32_bf16 v[56:59], v[162:165], v[216:219], v[56:59]
	v_mfma_f32_16x16x32_bf16 v[44:47], v[68:71], v[224:227], v[44:47]
	v_mfma_f32_16x16x32_bf16 v[40:43], v[162:165], v[224:227], v[40:43]
	v_mfma_f32_16x16x32_bf16 v[12:15], v[68:71], v[242:245], v[12:15]
	v_mfma_f32_16x16x32_bf16 v[8:11], v[162:165], v[242:245], v[8:11]
	s_setprio 0
	s_setprio 1
	v_mfma_f32_16x16x32_bf16 v[22:25], v[166:169], v[182:185], v[22:25]
	v_mfma_f32_16x16x32_bf16 v[68:71], v[170:173], v[186:189], v[22:25]
	v_mfma_f32_16x16x32_bf16 v[22:25], v[174:177], v[182:185], v[26:29]
	v_mfma_f32_16x16x32_bf16 v[64:67], v[178:181], v[186:189], v[22:25]
	v_mfma_f32_16x16x32_bf16 v[22:25], v[166:169], v[212:215], v[52:55]
	v_mfma_f32_16x16x32_bf16 v[52:55], v[170:173], v[216:219], v[22:25]
	v_mfma_f32_16x16x32_bf16 v[22:25], v[174:177], v[212:215], v[48:51]
	v_mfma_f32_16x16x32_bf16 v[48:51], v[178:181], v[216:219], v[22:25]
	v_mfma_f32_16x16x32_bf16 v[22:25], v[166:169], v[220:223], v[36:39]
	v_mfma_f32_16x16x32_bf16 v[36:39], v[170:173], v[224:227], v[22:25]
	v_mfma_f32_16x16x32_bf16 v[22:25], v[174:177], v[220:223], v[30:33]
	v_mfma_f32_16x16x32_bf16 v[4:7], v[166:169], v[228:231], v[4:7]
	v_mfma_f32_16x16x32_bf16 v[0:3], v[174:177], v[228:231], v[0:3]
	v_mfma_f32_16x16x32_bf16 v[32:35], v[178:181], v[224:227], v[22:25]
	v_mfma_f32_16x16x32_bf16 v[4:7], v[170:173], v[242:245], v[4:7]
	v_mfma_f32_16x16x32_bf16 v[0:3], v[178:181], v[242:245], v[0:3]
	s_setprio 0
	s_barrier
	s_cmp_lt_u32 s71, 12
	s_cbranch_scc0 .Ledge_slow_mixin
	s_mov_b64 s[40:41], 0
	s_branch .LBB0_393
.Ledge_slow_mixin:
	s_cmp_gt_u32 s71, 13
	s_cbranch_scc1 .LBB0_397
